# P8 LayerNorm loop rewritten: all row loads issued together, ln_g/ln_b hoisted out of the row loop, DPP for intra-row reductions
# speedup vs baseline: 1.0377x; 1.0252x over previous
; DEV float bflo(unsigned u) { return __uint_as_float(u << 16); }
; DEV float bfhi(unsigned u) { return __uint_as_float(u & 0xffff0000u); }
; DEV int otid() { int t = threadIdx.x; asm volatile("" : "+v"(t)); return t; }
; DEV int obid() { int t = __builtin_amdgcn_readfirstlane(*(volatile int*)(smem_g + 147456 + 8)); asm volatile("" : "+s"(t)); return t; }
; DEV int onb() { int t = gridDim.x; asm volatile("" : "+s"(t)); return t; }
; DEV void phase8(const Params& p, int l) {
;     char* ws = p.ws;
;     const float* xin = l == 0 ? p.x : p.out; const bf16_t* o = (const bf16_t*)(ws + OFF_OUT);
;     const int wid = otid() >> 6, lane = otid() & 63;
;     const float alpha = 1.4142135623730951f;
;     for (int t = obid() * 8 + wid; t < T_TOK; t += onb() * 8) {
;         f32x4 v[4]; float sm = 0.f;
; #pragma unroll
;         for (int j = 0; j < 4; ++j) { const int col = j * 256 + lane * 4; const f32x4 xv = *(const f32x4*)(xin + (size_t)t * 1024 + col); const u32x2 ov = *(const u32x2*)(o + (size_t)t * 1024 + col);
;             v[j] = xv * alpha + (f32x4){bflo(ov[0]), bfhi(ov[0]), bflo(ov[1]), bfhi(ov[1])}; sm += (v[j][0] + v[j][1]) + (v[j][2] + v[j][3]); }
;         const float mean = wave_sum(sm) * (1.0f / 1024.0f); float sq = 0.f;
; #pragma unroll
;         for (int j = 0; j < 4; ++j) { v[j] -= mean; sq += (v[j][0] * v[j][0] + v[j][1] * v[j][1]) + (v[j][2] * v[j][2] + v[j][3] * v[j][3]); }
;         const float rstd = rsqrtf(wave_sum(sq) * (1.0f / 1024.0f) + 1e-5f);
; #pragma unroll
;         for (int j = 0; j < 4; ++j) { const int col = j * 256 + lane * 4; const f32x4 g = *(const f32x4*)(p.ln_g + l * 1024 + col), bb = *(const f32x4*)(p.ln_b + l * 1024 + col);
.LBB0_932:
	s_or_b64 exec, exec, s[0:1]
	v_readlane_b32 s2, v243, 4
	v_readlane_b32 s4, v243, 5
	s_cmp_lg_u32 s2, -1
	v_readlane_b32 s5, v243, 6
	s_cselect_b32 s2, s2, 0
	s_cselect_b32 s3, s5, 0
	s_mov_b64 s[0:1], s[52:53]
	v_mov_b32_e32 v1, v163
	s_waitcnt lgkmcnt(0)
	v_mov_b32_e32 v0, v163
	v_mov_b32_e32 v2, s2
	v_mov_b32_e32 v3, s3
	s_barrier
	flat_load_dword v2, v[2:3] sc0 sc1
	s_waitcnt vmcnt(0)
	v_ashrrev_i32_e32 v1, 6, v1
	s_waitcnt lgkmcnt(0)
	v_readfirstlane_b32 s2, v2
	s_nop 1
	v_lshl_add_u32 v4, s2, 3, v1
	s_mov_b32 s2, 0x10000
	v_cmp_gt_i32_e32 vcc, s2, v4
	s_and_saveexec_b64 s[2:3], vcc
	s_cbranch_execz .LBB0_943
	v_lshlrev_b32_e32 v0, 2, v0
	v_and_b32_e32 v6, 0xfc, v0
	v_and_b32_e32 v0, 64, v183
	v_add_u32_e32 v0, 64, v0
	v_xor_b32_e32 v1, 32, v183
	v_cmp_lt_i32_e32 vcc, v1, v0
	s_load_dwordx2 s[4:5], s[0:1], 0x0
	s_load_dwordx8 s[40:47], s[0:1], 0xd0
	v_cndmask_b32_e32 v1, v183, v1, vcc
	v_lshlrev_b32_e32 v7, 2, v1
	v_xor_b32_e32 v1, 16, v183
	v_cmp_lt_i32_e32 vcc, v1, v0
	s_and_b64 s[0:1], s[18:19], exec
	s_waitcnt lgkmcnt(0)
	s_cselect_b32 s1, s5, s45
	v_cndmask_b32_e32 v1, v183, v1, vcc
	v_lshlrev_b32_e32 v36, 2, v1
	v_xor_b32_e32 v1, 8, v183
	v_cmp_lt_i32_e32 vcc, v1, v0
	s_cselect_b32 s0, s4, s44
	v_readlane_b32 s4, v243, 63
	v_cndmask_b32_e32 v1, v183, v1, vcc
	v_lshlrev_b32_e32 v37, 2, v1
	v_xor_b32_e32 v1, 4, v183
	v_cmp_lt_i32_e32 vcc, v1, v0
	s_lshl_b32 s10, s4, 10
	v_readlane_b32 s5, v242, 0
	v_cndmask_b32_e32 v1, v183, v1, vcc
	v_lshlrev_b32_e32 v38, 2, v1
	v_xor_b32_e32 v1, 2, v183
	v_cmp_lt_i32_e32 vcc, v1, v0
	s_add_u32 s6, s46, 0x369b0000
	s_addc_u32 s7, s47, 0
	v_cndmask_b32_e32 v1, v183, v1, vcc
	v_lshlrev_b32_e32 v39, 2, v1
	v_xor_b32_e32 v1, 1, v183
	s_lshl_b64 s[4:5], s[10:11], 2
	v_cmp_lt_i32_e32 vcc, v1, v0
	s_add_u32 s8, s40, s4
	s_addc_u32 s9, s41, s5
	v_cndmask_b32_e32 v0, v183, v1, vcc
	v_lshlrev_b32_e32 v40, 2, v0
	v_lshlrev_b32_e32 v160, 2, v6
	s_add_u32 s4, s42, s4
	v_lshlrev_b32_e32 v0, 1, v6
	v_mov_b32_e32 v1, v161
	s_addc_u32 s5, s43, s5
	v_lshl_add_u64 v[12:13], s[0:1], 0, v[160:161]
	v_lshl_add_u64 v[0:1], s[46:47], 0, v[0:1]
	s_mov_b64 s[0:1], 0x219b0000
	v_lshl_add_u64 v[8:9], s[8:9], 0, v[160:161]
	v_lshl_add_u64 v[10:11], s[4:5], 0, v[160:161]
	v_lshl_add_u64 v[14:15], v[0:1], 0, s[0:1]
	v_lshl_add_u64 v[16:17], s[44:45], 0, v[160:161]
	s_mov_b64 s[8:9], 0
	global_load_dwordx4 v[104:107], v[8:9], off
	global_load_dwordx4 v[108:111], v[8:9], off offset:1024
	global_load_dwordx4 v[112:115], v[8:9], off offset:2048
	global_load_dwordx4 v[116:119], v[8:9], off offset:3072
	global_load_dwordx4 v[120:123], v[10:11], off
	global_load_dwordx4 v[124:127], v[10:11], off offset:1024
	global_load_dwordx4 v[128:131], v[10:11], off offset:2048
	global_load_dwordx4 v[132:135], v[10:11], off offset:3072
	s_branch .LBB0_935

; DEV float bflo(unsigned u) { return __uint_as_float(u << 16); }
; DEV float bfhi(unsigned u) { return __uint_as_float(u & 0xffff0000u); }
; DEV int obid() { int t = __builtin_amdgcn_readfirstlane(*(volatile int*)(smem_g + 147456 + 8)); asm volatile("" : "+s"(t)); return t; }
; DEV int onb() { int t = gridDim.x; asm volatile("" : "+s"(t)); return t; }
; DEV void store4(bf16_t* p, f32x4 v) { *(u32x2*)p = (u32x2){pk_bf16(v[0], v[1]), pk_bf16(v[2], v[3])}; }
; DEV void phase8(const Params& p, int l) {
;     ...
;     for (int t = obid() * 8 + wid; t < T_TOK; t += onb() * 8) {
;         f32x4 v[4]; float sm = 0.f;
; #pragma unroll
;         for (int j = 0; j < 4; ++j) { const int col = j * 256 + lane * 4; const f32x4 xv = *(const f32x4*)(xin + (size_t)t * 1024 + col); const u32x2 ov = *(const u32x2*)(o + (size_t)t * 1024 + col);
;             v[j] = xv * alpha + (f32x4){bflo(ov[0]), bfhi(ov[0]), bflo(ov[1]), bfhi(ov[1])}; sm += (v[j][0] + v[j][1]) + (v[j][2] + v[j][3]); }
;         const float mean = wave_sum(sm) * (1.0f / 1024.0f); float sq = 0.f;
; #pragma unroll
;         for (int j = 0; j < 4; ++j) { v[j] -= mean; sq += (v[j][0] * v[j][0] + v[j][1] * v[j][1]) + (v[j][2] * v[j][2] + v[j][3] * v[j][3]); }
;         const float rstd = rsqrtf(wave_sum(sq) * (1.0f / 1024.0f) + 1e-5f);
; #pragma unroll
;         for (int j = 0; j < 4; ++j) { const int col = j * 256 + lane * 4; const f32x4 g = *(const f32x4*)(p.ln_g + l * 1024 + col), bb = *(const f32x4*)(p.ln_b + l * 1024 + col);
;             const f32x4 ov = v[j] * rstd * g + bb;
;             *(f32x4*)(p.out + (size_t)t * 1024 + col) = ov;
;             if (l == 0) store4((bf16_t*)(ws + OFF_XB1) + (size_t)t * 1024 + col, ov); }
;     }
.LBB0_935:
	v_ashrrev_i32_e32 v5, 31, v4
	v_lshlrev_b64 v[18:19], 11, v[4:5]
	v_lshlrev_b64 v[32:33], 12, v[4:5]
	v_lshl_add_u64 v[46:47], v[14:15], 0, v[18:19]
	v_lshl_add_u64 v[42:43], v[12:13], 0, v[32:33]
	v_lshl_add_u64 v[32:33], v[16:17], 0, v[32:33]
	global_load_dwordx4 v[136:139], v[42:43], off
	global_load_dwordx4 v[140:143], v[42:43], off offset:1024
	global_load_dwordx4 v[144:147], v[42:43], off offset:2048
	global_load_dwordx4 v[148:151], v[42:43], off offset:3072
	global_load_dwordx2 v[152:153], v[46:47], off
	global_load_dwordx2 v[154:155], v[46:47], off offset:512
	global_load_dwordx2 v[156:157], v[46:47], off offset:1024
	global_load_dwordx2 v[158:159], v[46:47], off offset:1536
	s_waitcnt vmcnt(0)
	v_lshlrev_b32_e32 v0, 16, v152
	v_and_b32_e32 v1, 0xffff0000, v152
	v_lshlrev_b32_e32 v2, 16, v153
	v_and_b32_e32 v3, 0xffff0000, v153
	v_pk_fma_f32 v[136:137], v[136:137], s[22:23], v[0:1] op_sel_hi:[1,0,1]
	v_pk_fma_f32 v[138:139], v[138:139], s[22:23], v[2:3] op_sel_hi:[1,0,1]
	v_lshlrev_b32_e32 v0, 16, v154
	v_and_b32_e32 v1, 0xffff0000, v154
	v_lshlrev_b32_e32 v2, 16, v155
	v_and_b32_e32 v3, 0xffff0000, v155
	v_pk_fma_f32 v[140:141], v[140:141], s[22:23], v[0:1] op_sel_hi:[1,0,1]
	v_pk_fma_f32 v[142:143], v[142:143], s[22:23], v[2:3] op_sel_hi:[1,0,1]
	v_lshlrev_b32_e32 v0, 16, v156
	v_and_b32_e32 v1, 0xffff0000, v156
	v_lshlrev_b32_e32 v2, 16, v157
	v_and_b32_e32 v3, 0xffff0000, v157
	v_pk_fma_f32 v[144:145], v[144:145], s[22:23], v[0:1] op_sel_hi:[1,0,1]
	v_pk_fma_f32 v[146:147], v[146:147], s[22:23], v[2:3] op_sel_hi:[1,0,1]
	v_lshlrev_b32_e32 v0, 16, v158
	v_and_b32_e32 v1, 0xffff0000, v158
	v_lshlrev_b32_e32 v2, 16, v159
	v_and_b32_e32 v3, 0xffff0000, v159
	v_pk_fma_f32 v[148:149], v[148:149], s[22:23], v[0:1] op_sel_hi:[1,0,1]
	v_pk_fma_f32 v[150:151], v[150:151], s[22:23], v[2:3] op_sel_hi:[1,0,1]
	v_pk_add_f32 v[20:21], v[136:137], v[138:139]
	v_pk_add_f32 v[22:23], v[140:141], v[142:143]
	v_pk_add_f32 v[24:25], v[144:145], v[146:147]
	v_pk_add_f32 v[26:27], v[148:149], v[150:151]
	v_pk_add_f32 v[20:21], v[20:21], v[22:23]
	v_pk_add_f32 v[24:25], v[24:25], v[26:27]
	v_pk_add_f32 v[20:21], v[20:21], v[24:25]
	s_nop 0
	v_add_f32_e32 v5, v20, v21
	s_nop 1
	v_add_f32_dpp v5, v5, v5 quad_perm:[1,0,3,2] row_mask:0xf bank_mask:0xf bound_ctrl:1
	s_nop 1
	v_add_f32_dpp v5, v5, v5 quad_perm:[2,3,0,1] row_mask:0xf bank_mask:0xf bound_ctrl:1
	s_nop 1
	v_add_f32_dpp v5, v5, v5 row_half_mirror row_mask:0xf bank_mask:0xf bound_ctrl:1
	s_nop 1
	v_add_f32_dpp v5, v5, v5 row_mirror row_mask:0xf bank_mask:0xf bound_ctrl:1
	ds_bpermute_b32 v34, v36, v5
	s_waitcnt lgkmcnt(0)
	v_add_f32_e32 v5, v5, v34
	ds_bpermute_b32 v34, v7, v5
	s_waitcnt lgkmcnt(0)
	v_add_f32_e32 v5, v5, v34
	v_mul_f32_e32 v20, 0xba800000, v5
	v_pk_add_f32 v[136:137], v[136:137], v[20:21] op_sel_hi:[1,0]
	v_pk_add_f32 v[138:139], v[138:139], v[20:21] op_sel_hi:[1,0]
	v_pk_add_f32 v[140:141], v[140:141], v[20:21] op_sel_hi:[1,0]
	v_pk_add_f32 v[142:143], v[142:143], v[20:21] op_sel_hi:[1,0]
	v_pk_add_f32 v[144:145], v[144:145], v[20:21] op_sel_hi:[1,0]
	v_pk_add_f32 v[146:147], v[146:147], v[20:21] op_sel_hi:[1,0]
	v_pk_add_f32 v[148:149], v[148:149], v[20:21] op_sel_hi:[1,0]
	v_pk_add_f32 v[150:151], v[150:151], v[20:21] op_sel_hi:[1,0]
	v_pk_mul_f32 v[22:23], v[136:137], v[136:137]
	v_pk_mul_f32 v[24:25], v[138:139], v[138:139]
	v_pk_fma_f32 v[22:23], v[140:141], v[140:141], v[22:23]
	v_pk_fma_f32 v[24:25], v[142:143], v[142:143], v[24:25]
	v_pk_fma_f32 v[22:23], v[144:145], v[144:145], v[22:23]
	v_pk_fma_f32 v[24:25], v[146:147], v[146:147], v[24:25]
	v_pk_fma_f32 v[22:23], v[148:149], v[148:149], v[22:23]
	v_pk_fma_f32 v[24:25], v[150:151], v[150:151], v[24:25]
	v_pk_add_f32 v[22:23], v[22:23], v[24:25]
	s_nop 0
	v_add_f32_e32 v5, v22, v23
	s_nop 1
	v_add_f32_dpp v5, v5, v5 quad_perm:[1,0,3,2] row_mask:0xf bank_mask:0xf bound_ctrl:1
	s_nop 1
	v_add_f32_dpp v5, v5, v5 quad_perm:[2,3,0,1] row_mask:0xf bank_mask:0xf bound_ctrl:1
	s_nop 1
	v_add_f32_dpp v5, v5, v5 row_half_mirror row_mask:0xf bank_mask:0xf bound_ctrl:1
	s_nop 1
	v_add_f32_dpp v5, v5, v5 row_mirror row_mask:0xf bank_mask:0xf bound_ctrl:1
	ds_bpermute_b32 v34, v36, v5
	s_waitcnt lgkmcnt(0)
	v_add_f32_e32 v5, v5, v34
	ds_bpermute_b32 v34, v7, v5
	s_waitcnt lgkmcnt(0)
	v_add_f32_e32 v5, v5, v34
	v_fmamk_f32 v5, v5, 0x3a800000, v179
	v_rsq_f32_e32 v34, v5
	s_nop 1
	v_pk_mul_f32 v[136:137], v[136:137], v[34:35] op_sel_hi:[1,0]
	v_pk_mul_f32 v[138:139], v[138:139], v[34:35] op_sel_hi:[1,0]
	v_pk_mul_f32 v[140:141], v[140:141], v[34:35] op_sel_hi:[1,0]
	v_pk_mul_f32 v[142:143], v[142:143], v[34:35] op_sel_hi:[1,0]
	v_pk_mul_f32 v[144:145], v[144:145], v[34:35] op_sel_hi:[1,0]
	v_pk_mul_f32 v[146:147], v[146:147], v[34:35] op_sel_hi:[1,0]
	v_pk_mul_f32 v[148:149], v[148:149], v[34:35] op_sel_hi:[1,0]
	v_pk_mul_f32 v[150:151], v[150:151], v[34:35] op_sel_hi:[1,0]
	v_pk_fma_f32 v[136:137], v[136:137], v[104:105], v[120:121]
	v_pk_fma_f32 v[138:139], v[138:139], v[106:107], v[122:123]
	v_pk_fma_f32 v[140:141], v[140:141], v[108:109], v[124:125]
	v_pk_fma_f32 v[142:143], v[142:143], v[110:111], v[126:127]
	v_pk_fma_f32 v[144:145], v[144:145], v[112:113], v[128:129]
	v_pk_fma_f32 v[146:147], v[146:147], v[114:115], v[130:131]
	v_pk_fma_f32 v[148:149], v[148:149], v[116:117], v[132:133]
	v_pk_fma_f32 v[150:151], v[150:151], v[118:119], v[134:135]
	global_store_dwordx4 v[32:33], v[136:139], off
	global_store_dwordx4 v[32:33], v[140:143], off offset:1024
	global_store_dwordx4 v[32:33], v[144:147], off offset:2048
	global_store_dwordx4 v[32:33], v[148:151], off offset:3072
	s_and_b64 vcc, exec, s[38:39]
	s_cbranch_vccnz .LBB0_934
	v_lshl_add_u64 v[18:19], s[6:7], 0, v[18:19]
	v_lshlrev_b32_e32 v160, 1, v6
	v_lshl_add_u64 v[18:19], v[18:19], 0, v[160:161]
	v_cvt_pk_bf16_f32 v0, v136, v137
	v_cvt_pk_bf16_f32 v1, v138, v139
	global_store_dwordx2 v[18:19], v[0:1], off
	v_cvt_pk_bf16_f32 v2, v140, v141
	v_cvt_pk_bf16_f32 v3, v142, v143
	global_store_dwordx2 v[18:19], v[2:3], off offset:512
	v_cvt_pk_bf16_f32 v20, v144, v145
	v_cvt_pk_bf16_f32 v21, v146, v147
	global_store_dwordx2 v[18:19], v[20:21], off offset:1024
	v_cvt_pk_bf16_f32 v22, v148, v149
	v_cvt_pk_bf16_f32 v23, v150, v151
	global_store_dwordx2 v[18:19], v[22:23], off offset:1536
	s_branch .LBB0_934
